# HGRN2 decay chain: lane-to-column ownership permuted (even columns on lanes 0-31, odd on 32-63) so each half-wave's bf16 LDS image writes hit distinct dwords; partial-sum exchange keyed by the permute
# baseline (speedup 1.0000x reference)
; template <int DK, int DVS, bool RET> ...
;     ...
;     const int wid = tid >> 6, lane = tid & 63, l16 = lane & 15, quad = lane >> 4;
;     const int tr = wid >> 1, tv = wid / WPV, kt0 = (wid % WPV) * TPW;
;     const int vtr = (int)aVI + (8 * quad + (l16 >> 2)) * (LV * 2) + 8 * (lane & 3);
;     const int ktr = (int)aKD + (8 * quad + (l16 >> 2)) * (LK * 2) + 8 * (lane & 3);
;     ...
;     f32x4 st[TPW];
; #pragma unroll
;     for (int t = 0; t < TPW; ++t) st[t] = (f32x4){0.f, 0.f, 0.f, 0.f};
;     ...
;     typedef short vvec_t __attribute__((ext_vector_type(VPT)));
;     constexpr int NQV = RET ? 4 : 1, NLC = RET ? 1 : PPT;
;     bf16x8 qv[NQV], kv[NQV]; float lc[NLC]; bf16_t qr[NLC]; vvec_t vraw;
;     const int kx = tid % DK, pg = tid / DK;
.LBB0_48:
	s_andn2_b64 vcc, exec, s[14:15]
	s_cbranch_vccnz .LBB0_59
	s_cmpk_gt_i32 s2, 0xff
	s_cbranch_scc1 .LBB0_59
	v_ashrrev_i32_e32 v2, 6, v146
	s_waitcnt lgkmcnt(0)
	v_lshrrev_b32_e32 v1, 30, v2
	v_add_u32_e32 v1, v2, v1
	v_bfe_u32 v0, v146, 4, 2
	v_ashrrev_i32_e32 v3, 2, v1
	v_and_b32_e32 v1, -4, v1
	s_waitcnt vmcnt(0)
	v_sub_u32_e32 v4, v2, v1
	v_lshlrev_b32_e32 v9, 3, v0
	v_bfe_u32 v1, v146, 2, 2
	v_or_b32_e32 v5, v9, v1
	v_lshlrev_b32_e32 v1, 3, v146
	v_and_b32_e32 v1, 24, v1
	s_movk_i32 s6, 0x50
	v_mad_u32_u24 v76, v5, s6, v1
	v_ashrrev_i32_e32 v1, 31, v146
	v_lshrrev_b32_e32 v1, 25, v1
	v_lshlrev_b32_e32 v7, 2, v0
	v_lshlrev_b32_e32 v0, 2, v146
	v_add_u32_e32 v1, v146, v1
	v_and_b32_e32 v0, 28, v0
	v_ashrrev_i32_e32 v6, 7, v1
	v_and_b32_e32 v1, 0xffffff80, v1
	v_lshlrev_b32_e32 v14, 1, v0
	v_mov_b32_e32 v15, v145
	v_sub_u32_e32 v10, v146, v1
	v_and_b32_e32 v11, 31, v10
	v_bfe_u32 v12, v10, 5, 1
	v_and_b32_e32 v13, 64, v10
	v_lshl_or_b32 v11, v11, 1, v12
	v_or_b32_e32 v10, v11, v13
	v_lshl_add_u64 v[0:1], s[0:1], 0, v[14:15]
	s_mov_b64 s[6:7], 0xbf69000
	v_ashrrev_i32_e32 v93, 3, v146
	v_lshl_add_u64 v[16:17], v[0:1], 0, s[6:7]
	v_add_u32_e32 v0, 0x7f, v146
	v_ashrrev_i32_e32 v11, 31, v10
	v_cmp_gt_u32_e32 vcc, s43, v0
	v_and_b32_e32 v0, 1, v2
	v_bfi_b32 v2, -16, v93, v146
	s_movk_i32 s7, 0x110
	s_movk_i32 s16, 0x90
	s_movk_i32 s14, 0x880
	v_lshlrev_b32_e32 v77, 4, v6
	v_lshl_or_b32 v18, v3, 4, v7
	v_mul_lo_u32 v94, v2, s7
	v_mul_lo_u32 v99, v2, s16
	v_lshlrev_b32_e32 v100, 5, v3
	v_mad_u64_u32 v[2:3], s[14:15], v6, s14, v[10:11]
	v_and_b32_e32 v8, 15, v146
	v_or_b32_e32 v78, 1, v77
	v_lshlrev_b32_e32 v15, 5, v0
	v_and_b32_e32 v1, -16, v93
	v_lshlrev_b32_e32 v0, 4, v0
	s_movk_i32 s14, 0x88
	v_or_b32_e32 v95, v15, v8
	v_or_b32_e32 v97, v7, v1
	v_or_b32_e32 v7, v0, v8
	s_movk_i32 s6, 0xc0
	v_mul_lo_u32 v103, v18, s7
	v_mad_u64_u32 v[18:19], s[14:15], v78, s14, v[10:11]
	s_add_u32 s3, s0, 0x10369000
	v_or_b32_e32 v1, 16, v95
	v_mul_u32_u24_e32 v98, 0x110, v7
	v_mad_u32_u24 v101, v5, s6, v76
	v_lshl_or_b32 v5, v4, 1, 1
	s_movk_i32 s6, 0x7f
	s_movk_i32 s10, 0x17f
	s_movk_i32 s12, 0x1ff
	v_add_u32_e32 v3, 0x88, v18
	v_add_u32_e32 v6, 0x110, v18
	v_add_u32_e32 v7, 0x198, v18
	v_add_u32_e32 v20, 0x220, v18
	v_add_u32_e32 v21, 0x2a8, v18
	v_add_u32_e32 v22, 0x330, v18
	v_add_u32_e32 v23, 0x3b8, v18
	v_add_u32_e32 v24, 0x440, v18
	v_add_u32_e32 v25, 0x4c8, v18
	v_add_u32_e32 v26, 0x550, v18
	v_add_u32_e32 v27, 0x5d8, v18
	v_add_u32_e32 v28, 0x660, v18
	v_add_u32_e32 v29, 0x6e8, v18
	v_add_u32_e32 v30, 0x770, v18
	v_mul_lo_u32 v19, v97, s16
	v_or_b32_e32 v105, 1, v97
	v_or_b32_e32 v107, 2, v97
	v_or_b32_e32 v109, 3, v97
	s_mov_b64 s[70:71], s[86:87]
	s_addc_u32 s48, s1, 0
	v_lshl_add_u64 v[12:13], v[10:11], 1, s[90:91]
	v_or_b32_e32 v79, 2, v77
	v_or_b32_e32 v80, 3, v77
	v_or_b32_e32 v81, 4, v77
	v_or_b32_e32 v82, 5, v77
	v_or_b32_e32 v83, 6, v77
	v_or_b32_e32 v84, 7, v77
	v_or_b32_e32 v85, 8, v77
	v_or_b32_e32 v86, 9, v77
	v_or_b32_e32 v87, 10, v77
	v_or_b32_e32 v88, 11, v77
	v_or_b32_e32 v89, 12, v77
	v_or_b32_e32 v90, 13, v77
	v_or_b32_e32 v91, 14, v77
	v_or_b32_e32 v92, 15, v77
	v_mul_u32_u24_e32 v96, 0x110, v95
	v_lshlrev_b32_e32 v102, 6, v4
	v_lshlrev_b32_e32 v104, 5, v5
	v_cmp_lt_i32_e64 s[6:7], s6, v146
	v_cmp_lt_i32_e64 s[8:9], s43, v146
	v_cmp_lt_i32_e64 s[10:11], s10, v146
	v_cmp_lt_i32_e64 s[12:13], s12, v146
	v_cmp_gt_i32_e64 s[14:15], v95, v97
	v_cmp_gt_i32_e64 s[16:17], v1, v97
	v_cmp_gt_i32_e64 s[18:19], v95, v105
	v_add_u32_e32 v106, 0x90, v19
	v_cmp_gt_i32_e64 s[20:21], v1, v105
	v_cmp_gt_i32_e64 s[22:23], v95, v107
	v_add_u32_e32 v108, 0x120, v19
	v_cmp_gt_i32_e64 s[24:25], v1, v107
	v_cmp_gt_i32_e64 s[26:27], v95, v109
	v_add_u32_e32 v250, 0x1b0, v19
	v_cmp_gt_i32_e64 s[28:29], v1, v109
	v_sub_u32_e32 v251, 63, v97
	v_sub_u32_e32 v252, 63, v105
	v_sub_u32_e32 v198, 63, v107
	v_sub_u32_e32 v114, 63, v109
	v_lshlrev_b32_e32 v115, 7, v4
	v_lshlrev_b32_e32 v116, 6, v5
	v_lshlrev_b32_e32 v144, 1, v0
	v_lshlrev_b32_e32 v117, 1, v2
	v_lshlrev_b32_e32 v118, 1, v3
	v_lshlrev_b32_e32 v119, 1, v6
	v_lshlrev_b32_e32 v120, 1, v7
	v_lshlrev_b32_e32 v121, 1, v20
	v_lshlrev_b32_e32 v122, 1, v21
	v_lshlrev_b32_e32 v123, 1, v22
	v_lshlrev_b32_e32 v124, 1, v23
	v_lshlrev_b32_e32 v125, 1, v24
	v_lshlrev_b32_e32 v126, 1, v25
	v_lshlrev_b32_e32 v127, 1, v26
	v_lshlrev_b32_e32 v128, 1, v27
	v_lshlrev_b32_e32 v129, 1, v28
	v_lshlrev_b32_e32 v130, 1, v29
	v_lshlrev_b32_e32 v131, 1, v30
	s_mov_b32 s49, s2
	s_cmp_lg_u32 s80, 0x100
	s_cbranch_scc1 .Lhg_noperm
	s_and_b32 s49, s2, 7
	s_lshl_b32 s49, s49, 5
	s_lshr_b32 s36, s2, 3
	s_or_b32 s49, s49, s36

; #define GAS __attribute__((address_space(1)))
; template <int DK, int DVS, bool RET> ...
;     ...
;     const int kx = tid % DK, pg = tid / DK;
;     const GAS bf16_t* Qg = (const GAS bf16_t*)Q; const GAS bf16_t* Kg = (const GAS bf16_t*)Kp; const GAS float* LFg = (const GAS float*)LF; const GAS bf16_t* Vg = (const GAS bf16_t*)V;
;     ...
;     GLA_LOAD(0);
.LBB0_52:
	s_bfe_i32 s36, s49, 0x10002
	s_bfe_u32 s63, s49, 0x10002
	s_ashr_i32 s40, s49, 6
	s_cmp_eq_u32 s63, 0
	s_cselect_b64 s[30:31], -1, 0
	s_and_b64 s[42:43], s[30:31], exec
	s_mov_b32 s42, 0x18b69000
	s_cselect_b32 s42, s42, 0x1ad69000
	s_add_u32 s56, s0, s42
	s_addc_u32 s57, s1, 0
	s_lshl_b32 s42, s49, 4
	s_and_b32 s66, s42, 0x380
	s_lshl_b32 s42, s49, 5
	s_and_b32 s42, s42, 0x60
	s_mov_b32 s41, 0
	s_or_b32 s62, s66, s42
	s_mul_hi_i32 s43, s40, 0x1100
	s_mul_i32 s42, s40, 0x1100
	s_and_b32 s40, s36, 0xc0
	s_or_b64 s[44:45], s[40:41], s[42:43]
	s_lshl_b32 s36, s63, 12
	s_add_u32 s36, s3, s36
	v_sub_u32_e32 v28, 63, v79
	s_addc_u32 s40, s48, 0
	s_lshl_b32 s63, s66, 2
	v_cndmask_b32_e64 v28, v28, v79, s[30:31]
	s_add_u32 s64, s36, s63
	v_ashrrev_i32_e32 v29, 31, v28
	s_addc_u32 s65, s40, 0
	s_lshl_b32 s36, s66, 1
	v_lshl_add_u64 v[30:31], s[44:45], 0, v[28:29]
	v_lshl_add_u64 v[24:25], v[12:13], 0, s[36:37]
	v_lshlrev_b64 v[32:33], 13, v[30:31]
	v_lshlrev_b64 v[30:31], 11, v[30:31]
	v_sub_u32_e32 v0, 63, v77
	v_lshl_add_u64 v[34:35], v[24:25], 0, v[30:31]
	v_sub_u32_e32 v30, 63, v80
	v_cndmask_b32_e64 v20, v0, v77, s[30:31]
	v_sub_u32_e32 v4, 63, v78
	v_cndmask_b32_e64 v30, v30, v80, s[30:31]
	v_ashrrev_i32_e32 v21, 31, v20
	v_cndmask_b32_e64 v26, v4, v78, s[30:31]
	v_ashrrev_i32_e32 v31, 31, v30
	v_lshl_add_u64 v[0:1], s[44:45], 0, v[20:21]
	v_ashrrev_i32_e32 v27, 31, v26
	v_lshl_add_u64 v[36:37], s[44:45], 0, v[30:31]
	v_lshl_add_u64 v[22:23], v[10:11], 2, s[64:65]
	v_lshlrev_b64 v[2:3], 13, v[0:1]
	v_lshl_add_u64 v[4:5], s[44:45], 0, v[26:27]
	v_lshlrev_b64 v[38:39], 13, v[36:37]
	v_lshlrev_b64 v[36:37], 11, v[36:37]
	v_readlane_b32 s59, v253, 62
	v_readlane_b32 s51, v254, 0
	v_readlane_b32 s47, v254, 2
	s_mov_b32 s50, s37
	v_readlane_b32 s46, v253, 63
	v_readlane_b32 s61, v254, 1
	v_readlane_b32 s60, v254, 3
	v_lshl_add_u64 v[2:3], v[22:23], 0, v[2:3]
	v_lshlrev_b64 v[0:1], 11, v[0:1]
	v_lshlrev_b64 v[6:7], 13, v[4:5]
	v_lshlrev_b64 v[4:5], 11, v[4:5]
	v_lshl_add_u64 v[36:37], v[24:25], 0, v[36:37]
	v_lshl_add_u64 v[0:1], v[24:25], 0, v[0:1]
	v_lshl_add_u64 v[6:7], v[22:23], 0, v[6:7]
	v_lshl_add_u64 v[4:5], v[24:25], 0, v[4:5]
	v_lshl_add_u64 v[32:33], v[22:23], 0, v[32:33]
	v_lshl_add_u64 v[38:39], v[22:23], 0, v[38:39]
	global_load_dword v132, v[2:3], off
	global_load_ushort v133, v[0:1], off
	global_load_dword v134, v[6:7], off
	global_load_ushort v135, v[4:5], off
	global_load_dword v136, v[32:33], off
	global_load_ushort v137, v[34:35], off
	global_load_dword v138, v[38:39], off
	global_load_ushort v139, v[36:37], off
	v_sub_u32_e32 v36, 63, v83
	v_cndmask_b32_e64 v36, v36, v83, s[30:31]
	v_ashrrev_i32_e32 v37, 31, v36
	v_lshl_add_u64 v[38:39], s[44:45], 0, v[36:37]
	v_lshlrev_b64 v[40:41], 13, v[38:39]
	v_lshlrev_b64 v[38:39], 11, v[38:39]
	v_sub_u32_e32 v0, 63, v81
	v_lshl_add_u64 v[42:43], v[24:25], 0, v[38:39]
	v_sub_u32_e32 v38, 63, v84
	v_cndmask_b32_e64 v32, v0, v81, s[30:31]
	v_sub_u32_e32 v4, 63, v82
	v_cndmask_b32_e64 v38, v38, v84, s[30:31]
	v_ashrrev_i32_e32 v33, 31, v32
	v_cndmask_b32_e64 v34, v4, v82, s[30:31]
	v_ashrrev_i32_e32 v39, 31, v38
	v_lshl_add_u64 v[0:1], s[44:45], 0, v[32:33]
	v_ashrrev_i32_e32 v35, 31, v34
	v_lshl_add_u64 v[44:45], s[44:45], 0, v[38:39]
	v_lshlrev_b64 v[2:3], 13, v[0:1]
	v_lshl_add_u64 v[4:5], s[44:45], 0, v[34:35]
	v_lshlrev_b64 v[46:47], 13, v[44:45]
	v_lshlrev_b64 v[44:45], 11, v[44:45]
	v_lshl_add_u64 v[2:3], v[22:23], 0, v[2:3]
	v_lshlrev_b64 v[0:1], 11, v[0:1]
	v_lshlrev_b64 v[6:7], 13, v[4:5]
	v_lshlrev_b64 v[4:5], 11, v[4:5]
	v_lshl_add_u64 v[44:45], v[24:25], 0, v[44:45]
	v_lshl_add_u64 v[0:1], v[24:25], 0, v[0:1]
	v_lshl_add_u64 v[6:7], v[22:23], 0, v[6:7]
	v_lshl_add_u64 v[4:5], v[24:25], 0, v[4:5]
	v_lshl_add_u64 v[40:41], v[22:23], 0, v[40:41]
	v_lshl_add_u64 v[46:47], v[22:23], 0, v[46:47]
	global_load_dword v140, v[2:3], off
	global_load_ushort v141, v[0:1], off
	global_load_dword v142, v[6:7], off
	global_load_ushort v143, v[4:5], off
	global_load_dword v147, v[40:41], off
	global_load_ushort v150, v[42:43], off
	global_load_dword v151, v[46:47], off
	global_load_ushort v162, v[44:45], off
	v_sub_u32_e32 v44, 63, v87
	v_cndmask_b32_e64 v44, v44, v87, s[30:31]
	v_ashrrev_i32_e32 v45, 31, v44
	v_lshl_add_u64 v[46:47], s[44:45], 0, v[44:45]
	v_lshlrev_b64 v[48:49], 13, v[46:47]
	v_lshlrev_b64 v[46:47], 11, v[46:47]
	v_sub_u32_e32 v0, 63, v85
	v_lshl_add_u64 v[50:51], v[24:25], 0, v[46:47]
	v_sub_u32_e32 v46, 63, v88
	v_cndmask_b32_e64 v40, v0, v85, s[30:31]
	v_sub_u32_e32 v4, 63, v86
	v_cndmask_b32_e64 v46, v46, v88, s[30:31]
	v_ashrrev_i32_e32 v41, 31, v40
	v_cndmask_b32_e64 v42, v4, v86, s[30:31]
	v_ashrrev_i32_e32 v47, 31, v46
	v_lshl_add_u64 v[0:1], s[44:45], 0, v[40:41]
	v_ashrrev_i32_e32 v43, 31, v42
	v_lshl_add_u64 v[52:53], s[44:45], 0, v[46:47]
	v_lshlrev_b64 v[2:3], 13, v[0:1]
	v_lshl_add_u64 v[4:5], s[44:45], 0, v[42:43]
	v_lshlrev_b64 v[54:55], 13, v[52:53]
	v_lshlrev_b64 v[52:53], 11, v[52:53]
	v_lshl_add_u64 v[2:3], v[22:23], 0, v[2:3]
	v_lshlrev_b64 v[0:1], 11, v[0:1]
	v_lshlrev_b64 v[6:7], 13, v[4:5]
	v_lshlrev_b64 v[4:5], 11, v[4:5]
	v_lshl_add_u64 v[52:53], v[24:25], 0, v[52:53]
	v_lshl_add_u64 v[0:1], v[24:25], 0, v[0:1]
	v_lshl_add_u64 v[6:7], v[22:23], 0, v[6:7]
	v_lshl_add_u64 v[4:5], v[24:25], 0, v[4:5]
	v_lshl_add_u64 v[48:49], v[22:23], 0, v[48:49]
	v_lshl_add_u64 v[54:55], v[22:23], 0, v[54:55]
	global_load_dword v210, v[2:3], off
	global_load_ushort v217, v[0:1], off
	global_load_dword v220, v[6:7], off
	global_load_ushort v221, v[4:5], off
	global_load_dword v222, v[48:49], off
	global_load_ushort v223, v[50:51], off
	global_load_dword v224, v[54:55], off
; #define LAS __attribute__((address_space(3)))
; #define GAS __attribute__((address_space(1)))
; template <int DK, int DVS, bool RET> ...
;     ...
;     unsigned aQD = (unsigned)(uintptr_t)(LAS unsigned char*)lds, aKD = aQD + 64 * LK * 2, aSTB = aKD + 64 * LK * 2, aVI = aSTB + DVS * LK * 2,
;              aAT = aVI + 64 * LV * 2, aEL = aAT + 64 * LS * 2, aTOT = aEL + DK * 4;
;     asm volatile("" : "+s"(aQD), "+s"(aVI), "+s"(aAT), "+s"(aEL), "+s"(aTOT), "+s"(aKD), "+s"(aSTB));
;     LAS bf16_t* QD = (LAS bf16_t*)(uintptr_t)aQD; LAS bf16_t* VI = (LAS bf16_t*)(uintptr_t)aVI; LAS bf16_t* AT = (LAS bf16_t*)(uintptr_t)aAT;
;     LAS float* EL = (LAS float*)(uintptr_t)aEL; LAS float* TOT = (LAS float*)(uintptr_t)aTOT;
;     LAS bf16_t* KD = (LAS bf16_t*)(uintptr_t)aKD; LAS bf16_t* STB = (LAS bf16_t*)(uintptr_t)aSTB;
;     static_assert(2 * 64 * LK * 2 + DVS * LK * 2 + 64 * LV * 2 + 64 * LS * 2 + DK * 4 + 2048 <= 159744, "GLA LDS map");
;     const int wid = tid >> 6, lane = tid & 63, l16 = lane & 15, quad = lane >> 4;
;     const int tr = wid >> 1, tv = wid / WPV, kt0 = (wid % WPV) * TPW;
;     const int vtr = (int)aVI + (8 * quad + (l16 >> 2)) * (LV * 2) + 8 * (lane & 3);
;     const int ktr = (int)aKD + (8 * quad + (l16 >> 2)) * (LK * 2) + 8 * (lane & 3);
;     ...
;     f32x4 st[TPW];
; #pragma unroll
;     for (int t = 0; t < TPW; ++t) st[t] = (f32x4){0.f, 0.f, 0.f, 0.f};
;     ...
;     typedef short vvec_t __attribute__((ext_vector_type(VPT)));
;     constexpr int NQV = RET ? 4 : 1, NLC = RET ? 1 : PPT;
;     bf16x8 qv[NQV], kv[NQV]; float lc[NLC]; bf16_t qr[NLC]; vvec_t vraw;
;     const int kx = tid % DK, pg = tid / DK;
;     const GAS bf16_t* Qg = (const GAS bf16_t*)Q; const GAS bf16_t* Kg = (const GAS bf16_t*)Kp; const GAS float* LFg = (const GAS float*)LF; const GAS bf16_t* Vg = (const GAS bf16_t*)V;
;     ...
;     GLA_LOAD(0);
	global_load_ushort v225, v[52:53], off
	v_sub_u32_e32 v52, 63, v91
	v_cndmask_b32_e64 v52, v52, v91, s[30:31]
	v_ashrrev_i32_e32 v53, 31, v52
	v_lshl_add_u64 v[54:55], s[44:45], 0, v[52:53]
	v_sub_u32_e32 v0, 63, v89
	v_lshlrev_b64 v[56:57], 13, v[54:55]
	v_lshlrev_b64 v[54:55], 11, v[54:55]
	v_cndmask_b32_e64 v48, v0, v89, s[30:31]
	v_sub_u32_e32 v4, 63, v90
	v_lshl_add_u64 v[58:59], v[24:25], 0, v[54:55]
	v_sub_u32_e32 v54, 63, v92
	v_ashrrev_i32_e32 v49, 31, v48
	v_cndmask_b32_e64 v50, v4, v90, s[30:31]
	v_cndmask_b32_e64 v54, v54, v92, s[30:31]
	v_lshl_add_u64 v[0:1], s[44:45], 0, v[48:49]
	v_ashrrev_i32_e32 v51, 31, v50
	v_ashrrev_i32_e32 v55, 31, v54
	v_lshlrev_b64 v[2:3], 13, v[0:1]
	v_lshl_add_u64 v[4:5], s[44:45], 0, v[50:51]
	v_lshl_add_u64 v[60:61], s[44:45], 0, v[54:55]
	v_lshl_add_u64 v[2:3], v[22:23], 0, v[2:3]
	v_lshlrev_b64 v[0:1], 11, v[0:1]
	v_lshlrev_b64 v[6:7], 13, v[4:5]
	v_lshlrev_b64 v[4:5], 11, v[4:5]
	v_lshlrev_b64 v[62:63], 13, v[60:61]
	v_lshlrev_b64 v[60:61], 11, v[60:61]
	v_lshl_add_u64 v[0:1], v[24:25], 0, v[0:1]
	v_lshl_add_u64 v[6:7], v[22:23], 0, v[6:7]
	v_lshl_add_u64 v[4:5], v[24:25], 0, v[4:5]
	v_lshl_add_u64 v[56:57], v[22:23], 0, v[56:57]
	v_lshl_add_u64 v[62:63], v[22:23], 0, v[62:63]
	v_lshl_add_u64 v[60:61], v[24:25], 0, v[60:61]
	global_load_dword v226, v[2:3], off
	global_load_ushort v227, v[0:1], off
	global_load_dword v228, v[6:7], off
	global_load_ushort v229, v[4:5], off
	global_load_dword v230, v[56:57], off
	global_load_ushort v231, v[58:59], off
	global_load_dword v232, v[62:63], off
	global_load_ushort v233, v[60:61], off
	v_sub_u32_e32 v2, 63, v93
	s_lshl_b32 s36, s62, 1
	v_cndmask_b32_e64 v56, v2, v93, s[30:31]
	v_lshlrev_b32_e32 v2, 2, v10
	s_movk_i32 s40, 0x50
	s_add_u32 s44, s56, s36
	v_lshlrev_b32_e32 v1, 1, v9
	v_lshlrev_b32_e32 v0, 1, v8
	v_add_u32_e32 v153, s61, v2
	v_add_u32_e32 v154, s51, v2
	v_mul_lo_u32 v2, v93, s40
	s_addc_u32 s45, s57, 0
	v_add_u32_e32 v4, s50, v1
	v_add_u32_e32 v5, s60, v0
	v_add3_u32 v155, s59, v2, v14
	v_add3_u32 v156, s47, v96, v1
	v_add_u32_e32 v6, s60, v1
	v_add3_u32 v158, s46, v99, v1
	v_lshl_add_u64 v[2:3], s[44:45], 0, v[144:145]
	v_mov_b32_e32 v1, v145
	v_add_u32_e32 v64, s59, v76
	v_lshl_add_u64 v[60:61], v[2:3], 0, v[0:1]
	v_add_u32_e32 v0, s47, v101
	v_add_u32_e32 v2, v5, v102
	v_add_u32_e32 v3, v5, v104
	v_lshlrev_b32_e32 v5, 1, v18
	v_add_u32_e32 v157, v64, v15
	v_add_u32_e32 v159, v64, v100
	v_lshl_add_u32 v1, v8, 2, s51
	v_add_u32_e32 v163, s50, v5
	v_add_u32_e32 v164, s47, v5
	v_lshlrev_b32_e32 v5, 1, v95
	v_cndmask_b32_e64 v62, v251, v97, s[30:31]
	v_cndmask_b32_e64 v64, v252, v105, s[30:31]
	v_cndmask_b32_e64 v66, v198, v107, s[30:31]
	v_cndmask_b32_e64 v68, v114, v109, s[30:31]
	v_add_u32_e32 v211, v0, v102
	v_add_u32_e32 v212, v0, v104
	v_mov_b32_e32 v0, 0
	v_ashrrev_i32_e32 v57, 31, v56
	v_lshl_add_u64 v[58:59], v[16:17], 0, s[36:37]
	v_and_b32_e32 v152, 0xffffff80, v146
	v_or_b32_e32 v152, v152, v10
	v_lshl_add_u32 v152, v152, 2, s61
	v_add_u32_e32 v160, s50, v117
	v_add_u32_e32 v161, s47, v117
	v_add_u32_e32 v165, s50, v118
	v_add_u32_e32 v166, s47, v118
	v_add_u32_e32 v167, s50, v119
	v_add_u32_e32 v168, s47, v119
	v_add_u32_e32 v169, s50, v120
	v_add_u32_e32 v170, s47, v120
	v_add_u32_e32 v171, s50, v121
	v_add_u32_e32 v172, s47, v121
	v_add_u32_e32 v173, s50, v122
	v_add_u32_e32 v174, s47, v122
	v_add_u32_e32 v175, s50, v123
	v_add_u32_e32 v176, s47, v123
	v_add_u32_e32 v177, s50, v124
	v_add_u32_e32 v178, s47, v124
	v_add_u32_e32 v179, s50, v125
	v_add_u32_e32 v180, s47, v125
	v_add_u32_e32 v181, s50, v126
	v_add_u32_e32 v182, s47, v126
	v_add_u32_e32 v183, s50, v127
	v_add_u32_e32 v184, s47, v127
	v_add_u32_e32 v185, s50, v128
	v_add_u32_e32 v199, s47, v128
	v_add_u32_e32 v200, s50, v129
	v_add_u32_e32 v201, s47, v129
	v_add_u32_e32 v202, s50, v130
	v_add_u32_e32 v203, s47, v130
	v_add_u32_e32 v204, s50, v131
	v_add_u32_e32 v205, s47, v131
	v_add3_u32 v206, s46, v19, v5
	v_add3_u32 v207, s46, v106, v5
	v_add3_u32 v208, s46, v108, v5
	v_add3_u32 v209, s46, v250, v5
	v_ashrrev_i32_e32 v63, 31, v62
	v_ashrrev_i32_e32 v65, 31, v64
	v_ashrrev_i32_e32 v67, 31, v66
	v_ashrrev_i32_e32 v69, 31, v68
	v_add_u32_e32 v213, v2, v103
	v_add_u32_e32 v214, v3, v103
	v_add_u32_e32 v215, v4, v94
	v_add_u32_e32 v216, v6, v98
	v_add_u32_e32 v218, v1, v115
	v_add_u32_e32 v219, v1, v116
	s_mov_b32 s36, s41
	v_mov_b32_e32 v1, v0
	v_mov_b32_e32 v2, v0
	v_mov_b32_e32 v3, v0
	v_mov_b32_e32 v4, v0
	v_mov_b32_e32 v5, v0
	v_mov_b32_e32 v6, v0
	v_mov_b32_e32 v7, v0
	v_mov_b32_e32 v71, v0
	v_mov_b32_e32 v72, v0
	v_mov_b32_e32 v73, v0
	v_mov_b32_e32 v74, v0
	v_mov_b32_e32 v75, v0
	v_mov_b32_e32 v234, v0
	v_mov_b32_e32 v70, v0
	v_lshlrev_b32_e32 v22, 2, v10
	v_add_lshl_u32 v23, s66, v10, 1
	v_lshl_add_u32 v21, v20, 11, v23
	v_lshl_add_u32 v20, v20, 13, v22
	v_lshl_add_u32 v27, v26, 11, v23
	v_lshl_add_u32 v26, v26, 13, v22
	v_lshl_add_u32 v29, v28, 11, v23
	v_lshl_add_u32 v28, v28, 13, v22
	v_lshl_add_u32 v31, v30, 11, v23
	v_lshl_add_u32 v30, v30, 13, v22
	v_lshl_add_u32 v33, v32, 11, v23
	v_lshl_add_u32 v32, v32, 13, v22
	v_lshl_add_u32 v35, v34, 11, v23
	v_lshl_add_u32 v34, v34, 13, v22
	v_lshl_add_u32 v37, v36, 11, v23
	v_lshl_add_u32 v36, v36, 13, v22
	v_lshl_add_u32 v39, v38, 11, v23
	v_lshl_add_u32 v38, v38, 13, v22
	v_lshl_add_u32 v41, v40, 11, v23
	v_lshl_add_u32 v40, v40, 13, v22
	v_lshl_add_u32 v43, v42, 11, v23
	v_lshl_add_u32 v42, v42, 13, v22
	v_lshl_add_u32 v45, v44, 11, v23
	v_lshl_add_u32 v44, v44, 13, v22
	v_lshl_add_u32 v47, v46, 11, v23
	v_lshl_add_u32 v46, v46, 13, v22
	v_lshl_add_u32 v49, v48, 11, v23
	v_lshl_add_u32 v48, v48, 13, v22
	v_lshl_add_u32 v51, v50, 11, v23
	v_lshl_add_u32 v50, v50, 13, v22
	v_lshl_add_u32 v53, v52, 11, v23
	v_lshl_add_u32 v52, v52, 13, v22
	v_lshl_add_u32 v55, v54, 11, v23
	v_lshl_add_u32 v54, v54, 13, v22
	s_branch .LBB0_54
